# v52: v51 + attention tile path trims stacked: SALU-derived skip flag (7.12), SGPR-base/32-bit-offset tile loads, tile-max chain without self-max, branch-free row select and out-of-line rescale
# speedup vs baseline: 1.0139x; 1.0045x over previous
; DI f32x16 mfma32(bf16x8 a, bf16x8 b, f32x16 c) { return __builtin_amdgcn_mfma_f32_32x32x16_bf16(a, b, c, 0, 0, 0); }
; template <int PM> DI void attn_phase(const Params& p, int l, char* smem, int* s_item, int wv, int cidx) {
;     ...
;         bool active = (PM != 1);
;         const int tpos = local_t0 + 64 * (i - nplain);
;         if (i >= nplain) {
;           if (mode == 1) active = (PM != 1) && (tpos + 63 >= tq0 - 128) && (tpos <= tq0 + 31 + 128);
;           else { const int dr = (tpos >> 6) - kr0; active = (PM != 1) && (dr >= 0 && dr < 8); }
;         }
;         f32x16 sacc[2];
;         if (active) {
; #pragma unroll
;           for (int kb = 0; kb < 2; ++kb)
; #pragma unroll
;             for (int e = 0; e < 16; ++e) sacc[kb][e] = 0.f;
;           const char* Kc = Kb0 + cur * 17408 + l31 * 272 + dofs_b + h * 16;
;           bf16x8 kf[8];
;           if (full_d) {
; #pragma unroll
;             for (int j = 0; j < 8; ++j) kf[j] = *(const bf16x8*)(Kc + (j >> 3) * 32 * 272 + (j & 7) * 32);
; #pragma unroll
;             for (int j = 0; j < 16; ++j) {
;               sacc[j >> 3] = mfma32(kf[j & 7], qf[j & 7], sacc[j >> 3]);
;               if (j + 8 < 16) kf[j & 7] = *(const bf16x8*)(Kc + ((j + 8) >> 3) * 32 * 272 + ((j + 8) & 7) * 32);
;               __builtin_amdgcn_sched_barrier(0);
;             }
.LBB0_435:
	s_andn2_b64 s[74:75], exec, s[2:3]
	s_andn2_b64 vcc, exec, s[2:3]
	s_mulk_i32 s95, 0x5000
	s_cbranch_vccnz .LBB0_441
	s_mulk_i32 s89, 0x4400
	v_add_u32_e32 v0, s89, v234
	ds_read_b128 v[48:51], v0
	ds_read_b128 v[10:13], v0 offset:32
	ds_read_b128 v[6:9], v0 offset:64
	ds_read_b128 v[2:5], v0 offset:96
	s_and_b64 vcc, exec, s[72:73]
	s_mov_b64 s[2:3], -1
	s_cbranch_vccnz .LBB0_438
	ds_read_b128 v[32:35], v0 offset:128
	ds_read_b128 v[36:39], v0 offset:160
	ds_read_b128 v[40:43], v0 offset:192
	ds_read_b128 v[44:47], v0 offset:224
	ds_read_b128 v[52:55], v0 offset:8704
	s_waitcnt lgkmcnt(8)
	v_mfma_f32_32x32x16_bf16 v[16:31], v[48:51], v[148:151], 0
	s_waitcnt lgkmcnt(7)
	v_mfma_f32_32x32x16_bf16 v[16:31], v[10:13], v[152:155], v[16:31]
	ds_read_b128 v[56:59], v0 offset:8736
	s_waitcnt lgkmcnt(7)
	v_mfma_f32_32x32x16_bf16 v[16:31], v[6:9], v[156:159], v[16:31]
	ds_read_b128 v[60:63], v0 offset:8768
	s_waitcnt lgkmcnt(7)
	v_mfma_f32_32x32x16_bf16 v[16:31], v[2:5], v[160:163], v[16:31]
	ds_read_b128 v[64:67], v0 offset:8800
	s_waitcnt lgkmcnt(7)
	v_mfma_f32_32x32x16_bf16 v[16:31], v[32:35], v[164:167], v[16:31]
	ds_read_b128 v[68:71], v0 offset:8832
	s_waitcnt lgkmcnt(7)
	v_mfma_f32_32x32x16_bf16 v[16:31], v[36:39], v[168:171], v[16:31]
	ds_read_b128 v[72:75], v0 offset:8864
	s_waitcnt lgkmcnt(7)
	v_mfma_f32_32x32x16_bf16 v[16:31], v[40:43], v[172:175], v[16:31]
	ds_read_b128 v[76:79], v0 offset:8896
	s_waitcnt lgkmcnt(7)
	v_mfma_f32_32x32x16_bf16 v[16:31], v[44:47], v[176:179], v[16:31]
	ds_read_b128 v[144:147], v0 offset:8928
	s_waitcnt lgkmcnt(7)
	v_mfma_f32_32x32x16_bf16 v[32:47], v[52:55], v[148:151], 0
	s_waitcnt lgkmcnt(6)
	v_mfma_f32_32x32x16_bf16 v[32:47], v[56:59], v[152:155], v[32:47]
	s_waitcnt lgkmcnt(5)
	v_mfma_f32_32x32x16_bf16 v[32:47], v[60:63], v[156:159], v[32:47]
	s_waitcnt lgkmcnt(4)
	v_mfma_f32_32x32x16_bf16 v[32:47], v[64:67], v[160:163], v[32:47]
	s_waitcnt lgkmcnt(3)
	v_mfma_f32_32x32x16_bf16 v[32:47], v[68:71], v[164:167], v[32:47]
	s_waitcnt lgkmcnt(2)
	v_mfma_f32_32x32x16_bf16 v[32:47], v[72:75], v[168:171], v[32:47]
	s_waitcnt lgkmcnt(1)
	v_mfma_f32_32x32x16_bf16 v[32:47], v[76:79], v[172:175], v[32:47]
	s_waitcnt lgkmcnt(0)
	v_mfma_f32_32x32x16_bf16 v[32:47], v[144:147], v[176:179], v[32:47]
	s_mov_b64 s[2:3], 0

; DI float fexp2(float x) { return __builtin_amdgcn_exp2f(x); }
; DI float half_max(float v) { const auto r = __builtin_amdgcn_permlane32_swap(__float_as_uint(v), __float_as_uint(v), false, false); return fmaxf(__uint_as_float(r[0]), __uint_as_float(r[1])); }
; template <int PM> DI void attn_phase(const Params& p, int l, char* smem, int* s_item, int wv, int cidx) {
;     ...
;           float mt = sacc[0][0];
; #pragma unroll
;           for (int e = 1; e < 16; ++e) mt = fmaxf(mt, sacc[0][e]);
; #pragma unroll
;           for (int e = 0; e < 16; ++e) mt = fmaxf(mt, sacc[1][e]);
;           mt = half_max(mt);
;           if (__builtin_amdgcn_ballot_w64(mt > m + 8.f) != 0ull) {
;             const float mnew = fmaxf(m, mt);
;             const float alpha = fexp2(m - mnew);
;             m = mnew;
;             lsum *= alpha;
; #pragma unroll
;             for (int db = 0; db < 4; ++db)
; #pragma unroll
;               for (int e = 0; e < 16; ++e) Oacc[db][e] *= alpha;
;           }
.LBB0_512:
	s_waitcnt lgkmcnt(2)
	v_max_f32_e32 v0, v16, v17
	v_max3_f32 v0, v0, v18, v19
	v_max3_f32 v0, v0, v20, v21
	v_max3_f32 v0, v0, v22, v23
	v_max3_f32 v0, v0, v24, v25
	v_max3_f32 v0, v0, v26, v27
	v_max3_f32 v0, v0, v28, v29
	v_max3_f32 v0, v0, v30, v31
	v_max3_f32 v0, v0, v32, v33
	v_max3_f32 v0, v0, v34, v35
	v_max3_f32 v0, v0, v36, v37
	v_max3_f32 v0, v0, v38, v39
	v_max3_f32 v0, v0, v40, v41
	v_max3_f32 v0, v0, v42, v43
	v_max3_f32 v0, v0, v44, v45
	v_max3_f32 v0, v0, v46, v47
	v_mov_b32_e32 v2, v0
	s_nop 1
	v_permlane32_swap_b32_e32 v0, v2
	v_max_f32_e32 v0, v0, v2
	v_add_f32_e32 v2, 0x41000000, v233
	v_cmp_gt_f32_e32 vcc, v0, v2
	s_cbranch_vccnz .Lst_resc
